# ret_kv-counter poll load issued before the attention phase's final store drain; kv2 waves' arrival add issued before the workgroup barrier and resolved after it
# baseline (speedup 1.0000x reference)
.LBB0_469:
	s_cmp_lg_u32 s98, 0
	s_cbranch_scc0 .Lb3_nopf
	v_readlane_b32 s99, v254, 25
	s_nop 3
	s_cmp_lg_u32 s99, 0
	s_cbranch_scc1 .Lb3_nopf
	s_mov_b64 s[100:101], exec
	s_mov_b64 exec, 1
	v_mov_b32_e32 v245, 0xfa0e000
	global_load_dword v245, v245, s[74:75] sc1
	buffer_inv sc1
	s_mov_b64 exec, s[100:101]
.Lb3_nopf:
	s_waitcnt vmcnt(0)
	v_readlane_b32 s66, v254, 22
	v_readlane_b32 s67, v254, 23
	v_readlane_b32 s72, v255, 2
	v_readlane_b32 s52, v254, 55
	s_and_b64 vcc, exec, s[66:67]
	v_readlane_b32 s70, v255, 10
	v_readlane_b32 s73, v255, 3
	v_readlane_b32 s53, v254, 56
	v_readlane_b32 s42, v254, 50
	s_waitcnt vmcnt(63) expcnt(7) lgkmcnt(15)
	s_barrier
	v_readlane_b32 s43, v254, 51
	s_cbranch_vccnz .LBB0_523
	s_cmp_lg_u32 s98, 0
	s_cbranch_scc0 .Lb3_orig
	s_mov_b64 s[100:101], exec
	s_mov_b64 exec, 1
	v_mov_b32_e32 v0, 0x21004
	ds_read_b32 v1, v0
	v_mov_b32_e32 v0, 0xfa0e000
	s_mov_b32 s99, 0
	s_waitcnt lgkmcnt(0)
	v_cmp_ge_u32_e32 vcc, v245, v1
	s_cbranch_vccnz .Lb3_done
	buffer_inv sc1

.LBB0_538:
	s_cmp_lg_u32 s98, 0
	s_cbranch_scc0 .Lp3_noarr
	s_waitcnt vmcnt(0)
	v_readlane_b32 s99, v254, 25
	v_readlane_b32 s100, v254, 24
	s_nop 3
	s_lshl_b32 s100, s100, 7
	s_cmp_ge_u32 s99, 4
	s_cbranch_scc1 .Lp3_kv
	s_cmp_ge_u32 s99, 4
	s_cselect_b32 s99, 0x900, 0
	s_add_i32 s99, s99, 0xfa0e100
	s_add_i32 s100, s100, s99
	v_mov_b32_e32 v0, s100
	s_add_i32 s99, s99, 0x800
	v_mov_b32_e32 v4, s99
	v_mov_b32_e32 v1, 1
	s_mov_b64 s[100:101], exec
	s_mov_b64 exec, 1
	v_mov_b32_e32 v3, 0x21000
	ds_read_b32 v3, v3
	global_atomic_add v2, v0, v1, s[74:75] sc0
	s_waitcnt vmcnt(0) lgkmcnt(0)
	v_add_u32_e32 v2, 1, v2
	v_lshlrev_b32_e32 v3, 2, v3
	v_cmp_eq_u32_e32 vcc, v2, v3
	s_cbranch_vccz .Lp3_arrd
	buffer_wbl2 sc1
	s_waitcnt vmcnt(0)
	global_atomic_add v4, v1, s[74:75]

.Lp3_kv:
	s_add_i32 s100, s100, 0xfa0ea00
	v_mov_b32_e32 v244, s100
	v_mov_b32_e32 v248, 0xfa0f200
	v_mov_b32_e32 v245, 1
	s_mov_b64 s[100:101], exec
	s_mov_b64 exec, 1
	v_mov_b32_e32 v247, 0x21000
	ds_read_b32 v247, v247
	global_atomic_add v246, v244, v245, s[74:75] sc0
	s_mov_b64 exec, s[100:101]
	s_branch .Lp3_pw

.Lp3_pw:
	s_and_b64 vcc, exec, s[66:67]
	s_barrier
	s_cbranch_vccnz .LBB0_592
	s_cmp_lg_u32 s98, 0
	s_cbranch_scc0 .Lb4_orig
	s_branch .LBB0_592

.LBB0_592:
	v_readlane_b32 s0, v254, 62
	v_readlane_b32 s1, v254, 63
	s_andn2_b64 vcc, exec, s[0:1]
	s_waitcnt lgkmcnt(0)
	v_cndmask_b32_e64 v0, 0, 1, s[0:1]
	v_cmp_ne_u32_e64 s[4:5], 1, v0
	s_barrier
	s_cmp_lg_u32 s98, 0
	s_cbranch_scc0 .Lp3_nochk
	v_readlane_b32 s99, v254, 25
	s_nop 3
	s_cmp_lt_u32 s99, 4
	s_cbranch_scc1 .Lp3_nochk
	s_waitcnt vmcnt(0) lgkmcnt(0)
	v_readfirstlane_b32 s99, v246
	v_readfirstlane_b32 s100, v247
	s_add_i32 s99, s99, 1
	s_lshl_b32 s100, s100, 2
	s_cmp_eq_u32 s99, s100
	s_cbranch_scc0 .Lp3_nochk
	buffer_wbl2 sc1
	s_waitcnt vmcnt(0)
	s_mov_b64 s[100:101], exec
	s_mov_b64 exec, 1
	global_atomic_add v248, v245, s[74:75]
	s_mov_b64 exec, s[100:101]
.Lp3_nochk:
	v_mbcnt_lo_u32_b32 v152, -1, 0
	v_mbcnt_hi_u32_b32 v152, -1, v152
	s_cbranch_vccnz .LBB0_598
	v_lshlrev_b32_e32 v7, 4, v152
	v_readlane_b32 s6, v254, 45
	v_and_b32_e32 v128, 0x70, v7
	v_mov_b32_e32 v129, 0
	v_readlane_b32 s7, v254, 46
	v_and_b32_e32 v0, 0xf0, v7
	v_mov_b32_e32 v1, v129
	v_lshl_add_u64 v[130:131], s[6:7], 0, v[128:129]
	v_readlane_b32 s6, v255, 0
	v_readlane_b32 s7, v255, 1
	v_lshrrev_b32_e32 v10, 1, v152
	v_and_b32_e32 v6, 31, v152
	v_lshl_add_u64 v[132:133], s[6:7], 0, v[0:1]
	v_lshlrev_b32_e32 v0, 1, v152
	v_and_b32_e32 v12, 19, v152
	v_and_b32_e32 v13, 8, v0
	v_and_b32_e32 v14, 4, v10
	v_ashrrev_i32_e32 v153, 5, v152
	v_readlane_b32 s0, v254, 48
	v_or_b32_e32 v134, s42, v6
	v_or3_b32 v0, v14, v12, v13
	s_lshl_b32 s0, s0, 16
	v_lshrrev_b32_e32 v15, 1, v0
	v_lshlrev_b32_e32 v0, 3, v153
	v_add_u32_e32 v1, 1, v134
	s_add_i32 s1, s0, 0
	v_readlane_b32 s2, v254, 52
	v_cvt_f32_ubyte0_e32 v157, v1
	v_ashrrev_i32_e32 v1, 31, v0
	v_readlane_b32 s7, v254, 53
	v_lshl_add_u32 v3, s2, 6, v152
	s_movk_i32 s3, 0x70
	v_bfe_u32 v11, v152, 1, 3
	v_lshl_add_u64 v[4:5], v[0:1], 2, s[8:9]
	s_add_i32 s2, s1, s7
	v_lshlrev_b32_e32 v1, 7, v6
	v_bitop3_b32 v8, v3, s3, v7 bitop3:0x48
	v_lshlrev_b32_e32 v2, 8, v6
	v_add3_u32 v159, s2, v1, v0
	v_lshlrev_b32_e32 v160, 4, v11
	v_ashrrev_i32_e32 v136, 3, v3
	v_ashrrev_i32_e32 v161, 4, v3
	v_add_u32_e32 v1, 0x100, v3
	v_add_u32_e32 v6, 0x200, v3
	v_add_u32_e32 v11, 0x300, v3
	v_lshlrev_b32_e32 v3, 4, v3
	s_movk_i32 s6, 0xff80
	v_and_or_b32 v17, v3, s6, v8
	v_xor_b32_e32 v3, v161, v152
	v_ashrrev_i32_e32 v162, 4, v1
	v_lshlrev_b32_e32 v3, 4, v3
	v_and_b32_e32 v19, 0xf0, v3
	v_xor_b32_e32 v3, v162, v152
	v_lshlrev_b32_e32 v3, 4, v3
	v_ashrrev_i32_e32 v163, 4, v6
	v_and_b32_e32 v21, 0xf0, v3
	v_lshlrev_b32_e32 v3, 4, v6
	v_ashrrev_i32_e32 v140, 3, v6
	v_and_or_b32 v6, v3, s6, v8
	v_xor_b32_e32 v3, v163, v152
	v_lshlrev_b32_e32 v3, 4, v3
	v_ashrrev_i32_e32 v138, 3, v1
	v_ashrrev_i32_e32 v164, 4, v11
	v_lshlrev_b32_e32 v1, 4, v1
	v_and_b32_e32 v23, 0xf0, v3
	v_lshlrev_b32_e32 v3, 4, v11
	v_and_or_b32 v1, v1, s6, v8
	v_and_or_b32 v8, v3, s6, v8
	v_xor_b32_e32 v3, v164, v152
	v_lshlrev_b32_e32 v3, 4, v3
	v_add_u32_e32 v16, 2, v153
	v_and_b32_e32 v24, 0xf0, v3
	v_bitop3_b32 v3, v10, v153, 7 bitop3:0x6c
	v_lshlrev_b32_e32 v25, 4, v3
	v_bitop3_b32 v3, v16, v10, 7 bitop3:0x78
	v_lshlrev_b32_e32 v26, 4, v3
	v_add_u32_e32 v3, 4, v153
	v_bitop3_b32 v27, v3, v10, 7 bitop3:0x78
	v_add_u32_e32 v28, 6, v153
	v_bitop3_b32 v3, v15, v3, 7 bitop3:0x6c
	v_lshlrev_b32_e32 v30, 4, v3
	v_bitop3_b32 v3, v15, v28, 7 bitop3:0x6c
	v_bitop3_b32 v29, v15, v153, 7 bitop3:0x6c
	v_bitop3_b32 v16, v15, v16, 7 bitop3:0x6c
	v_lshlrev_b32_e32 v15, 4, v3
	v_mov_b32_e32 v3, 0x70
	s_movk_i32 s6, 0x50
	v_bitop3_b32 v38, v7, s6, v3 bitop3:0x6c
	s_movk_i32 s6, 0x60
	v_bitop3_b32 v31, v7, 16, v3 bitop3:0x6c
	v_bitop3_b32 v33, v7, 32, v3 bitop3:0x6c
	v_bitop3_b32 v35, v7, 48, v3 bitop3:0x6c
	v_bitop3_b32 v36, v7, 64, v3 bitop3:0x6c
	v_bitop3_b32 v40, v7, s6, v3 bitop3:0x6c
	v_mov_b32_e32 v3, v129
	v_add_u32_e32 v155, s1, v2
	v_lshl_add_u64 v[150:151], v[4:5], 0, v[2:3]
	v_or3_b32 v2, v12, v13, v14
	v_lshl_or_b32 v2, v2, 7, s0
	v_add3_u32 v3, v2, v15, 0
	v_lshl_add_u32 v9, v134, 7, s1
	v_bitop3_b32 v10, v28, v10, 7 bitop3:0x78
	v_lshlrev_b32_e32 v29, 4, v29
	v_lshlrev_b32_e32 v16, 4, v16
	v_add_u32_e32 v165, 0x4000, v3
	v_add3_u32 v3, v2, v30, 0
	s_mov_b32 s61, 0
	v_sub_u32_e32 v154, 0, v0
	v_add_u32_e32 v158, v9, v0
	v_xor_b32_e32 v0, 64, v160
	v_ashrrev_i32_e32 v142, 3, v11
	v_lshl_add_u32 v18, v161, 8, s1
	v_lshl_add_u32 v20, v162, 8, s1
	v_lshl_add_u32 v22, v163, 8, s1
	v_lshl_add_u32 v11, v164, 8, s1
	v_lshlrev_b32_e32 v27, 4, v27
	v_lshlrev_b32_e32 v10, 4, v10
	v_xor_b32_e32 v28, 16, v160
	v_xor_b32_e32 v32, 32, v160
	v_xor_b32_e32 v34, 48, v160
	v_xor_b32_e32 v37, 0x50, v160
	v_xor_b32_e32 v39, 0x60, v160
	v_xor_b32_e32 v41, 0x70, v160
	v_bitop3_b32 v7, v7, s3, v7 bitop3:0xc
	v_add_u32_e32 v166, 0x4000, v3
	v_add3_u32 v3, v2, v16, 0
	v_add3_u32 v2, v2, v29, 0
	v_and_b32_e32 v156, 15, v152
	s_mov_b32 s43, s61
	v_ashrrev_i32_e32 v137, 31, v136
	v_ashrrev_i32_e32 v139, 31, v138
	v_ashrrev_i32_e32 v141, 31, v140
	v_ashrrev_i32_e32 v143, 31, v142
	v_add_u32_e32 v135, -1, v134
	v_add_u32_e32 v145, -3, v134
	v_add_u32_e32 v144, -2, v134
	v_add_u32_e32 v147, -5, v134
	v_add_u32_e32 v146, -4, v134
	v_add_u32_e32 v149, -7, v134
	v_add_u32_e32 v148, -6, v134
	s_add_i32 s3, s7, 0x1000
	v_add_u32_e32 v167, 0x4000, v3
	v_add_u32_e32 v168, 0x4000, v2
	s_mov_b32 s10, 0xc2fc0000
	v_mov_b32_e32 v169, 0x3ecc95a3
	s_movk_i32 s11, 0x1400
	v_add_u32_e32 v170, s1, v17
	v_add_u32_e32 v171, v18, v19
	v_add_u32_e32 v172, s1, v1
	v_add_u32_e32 v173, v20, v21
	v_add_u32_e32 v174, s1, v6
	v_add_u32_e32 v175, v22, v23
	v_add_u32_e32 v176, s1, v8
	v_add_u32_e32 v177, v11, v24
	v_add_u32_e32 v178, v9, v25
	v_add_u32_e32 v179, v9, v26
	v_add_u32_e32 v180, v9, v27
	v_add_u32_e32 v181, v9, v10
	s_mov_b32 s20, 0x5040100
	s_mov_b64 s[62:63], 0x2040
	s_mov_b64 s[64:65], 0x2080
	s_mov_b64 s[66:67], 0x20c0
	v_add_u32_e32 v182, v158, v28
	v_add_u32_e32 v183, v158, v32
	v_add_u32_e32 v184, v158, v34
	v_add_u32_e32 v185, v158, v0
	v_add_u32_e32 v186, v158, v37
	v_add_u32_e32 v187, v158, v39
	v_add_u32_e32 v188, v158, v41
	v_mov_b32_e32 v189, 0x358637bd
	s_mov_b32 s21, 0x800000
	v_add_u32_e32 v190, v159, v31
	v_add_u32_e32 v191, v159, v33
	v_add_u32_e32 v192, v159, v35
	v_add_u32_e32 v193, v159, v36
	v_add_u32_e32 v194, v159, v38
	v_add_u32_e32 v195, v159, v40
	v_add_u32_e32 v196, v159, v7
	v_mov_b32_e32 v197, 0x42800000
	v_mov_b32_e32 v198, 0x7fc00000
	v_mov_b32_e32 v199, 0xff800000
	v_not_b32_e32 v200, 63
	s_mov_b32 s33, s70
	s_mov_b32 s101, s78
	s_cmp_lg_u32 s98, 0
	s_cbranch_scc0 .Lro_nodeal
	s_and_b32 s99, s70, 7
	s_lshr_b32 s100, s70, 3
	s_lshr_b32 s33, s99, 2
	s_lshl_b32 s33, s33, 3
	s_lshr_b32 s101, s100, 2
	s_or_b32 s33, s33, s101
	s_lshl_b32 s33, s33, 5
	s_and_b32 s99, s99, 3
	s_lshl_b32 s99, s99, 3
	s_or_b32 s33, s33, s99
	s_and_b32 s100, s100, 3
	s_lshl_b32 s100, s100, 1
	s_or_b32 s33, s33, s100
	s_mov_b32 s101, 1
